# barriers: lane 0 issues the L1 acquire invalidate right behind its arrival atomic (overlaps the round trip; no cached loads between arrival and release)
# speedup vs baseline: 1.0199x; 1.0124x over previous
; __device__ __forceinline__ unsigned xb_add(unsigned* p, unsigned v) { return __hip_atomic_fetch_add(p, v, __ATOMIC_RELAXED, __HIP_MEMORY_SCOPE_AGENT); }
; __device__ __forceinline__ void xcd_barrier(const XcdBarrier& b) {
;     ...
;         const unsigned old = xb_add(&bar[XB_XSUB(b.x)], 1u);
;         const unsigned gen = old / nloc;
.LBB0_118:
	s_mov_b64 s[8:9], exec
	s_lshl_b32 s6, s87, 8
	v_readlane_b32 s10, v240, 0
	v_mbcnt_lo_u32_b32 v1, s8, 0
	v_readlane_b32 s11, v240, 1
	s_add_u32 s6, s10, s6
	v_mbcnt_hi_u32_b32 v1, s9, v1
	s_addc_u32 s7, s11, 0
	v_cmp_eq_u32_e32 vcc, 0, v1
	s_and_saveexec_b64 s[38:39], vcc
	s_cbranch_execz .LBB0_120
	s_bcnt1_i32_b64 s8, s[8:9]
	v_mov_b32_e32 v3, 0x1000
	v_mov_b32_e32 v4, s8
	global_atomic_add v3, v3, v4, s[6:7] offset:1024 sc0
	buffer_inv sc1

; __device__ __forceinline__ unsigned xb_ld(unsigned* p)              { return __hip_atomic_load(p, __ATOMIC_RELAXED, __HIP_MEMORY_SCOPE_AGENT); }
; #define XB_SPIN(cond, bar) do { unsigned _sp = 0; while (cond) { __builtin_amdgcn_s_sleep(1); \
;     if ((++_sp & 255u) == 0u) { if (xb_ld(&(bar)[XB_TMO])) break; if (_sp > XB_SPIN_CAP) { atomicAdd(&(bar)[XB_TMO], 1u); break; } } } } while (0)
; __device__ __forceinline__ void xcd_barrier(const XcdBarrier& b) {
;     ...
;             XB_SPIN(xb_ld(&bar[XB_XGEN(b.x)]) == gen, bar);
;             __builtin_amdgcn_fence(__ATOMIC_ACQUIRE, "agent");
;             asm volatile("s_waitcnt vmcnt(0)" ::: "memory");
.LBB0_133:
	s_or_b64 exec, exec, s[38:39]
	s_waitcnt vmcnt(0)
	s_waitcnt vmcnt(0)

; __device__ __forceinline__ unsigned xb_add(unsigned* p, unsigned v) { return __hip_atomic_fetch_add(p, v, __ATOMIC_RELAXED, __HIP_MEMORY_SCOPE_AGENT); }
; __device__ __forceinline__ void xcd_barrier(const XcdBarrier& b) {
;     ...
;             xb_add(&bar[XB_XGEN(b.x)], 1u);
;             asm volatile("s_waitcnt vmcnt(0)" ::: "memory");
.LBB0_151:
	s_or_b64 exec, exec, s[8:9]
	s_mov_b64 s[8:9], exec
	v_mbcnt_lo_u32_b32 v0, s8, 0
	v_mbcnt_hi_u32_b32 v0, s9, v0
	v_cmp_eq_u32_e32 vcc, 0, v0
	s_waitcnt vmcnt(0)
	s_and_saveexec_b64 s[38:39], vcc
	s_cbranch_execz .LBB0_153
	s_bcnt1_i32_b64 s8, s[8:9]
	v_mov_b32_e32 v0, 0x2000
	v_mov_b32_e32 v1, s8
	global_atomic_add v0, v1, s[6:7] offset:1024
.LBB0_153:
	s_or_b64 exec, exec, s[38:39]
	s_waitcnt vmcnt(0)

; __device__ __forceinline__ unsigned xb_add(unsigned* p, unsigned v) { return __hip_atomic_fetch_add(p, v, __ATOMIC_RELAXED, __HIP_MEMORY_SCOPE_AGENT); }
; __device__ __forceinline__ void xcd_barrier(const XcdBarrier& b) {
;     ...
;             xb_add(&bar[XB_XGEN(b.x)], 1u);
;             asm volatile("s_waitcnt vmcnt(0)" ::: "memory");
.LBB0_274:
	s_or_b64 exec, exec, s[8:9]
	s_mov_b64 s[8:9], exec
	v_mbcnt_lo_u32_b32 v0, s8, 0
	v_mbcnt_hi_u32_b32 v0, s9, v0
	v_cmp_eq_u32_e32 vcc, 0, v0
	s_waitcnt vmcnt(0)
	s_and_saveexec_b64 s[38:39], vcc
	s_cbranch_execz .LBB0_276
	s_bcnt1_i32_b64 s8, s[8:9]
	v_mov_b32_e32 v0, 0x2000
	v_mov_b32_e32 v1, s8
	global_atomic_add v0, v1, s[6:7] offset:1024
.LBB0_276:
	s_or_b64 exec, exec, s[38:39]
	s_waitcnt vmcnt(0)

; __device__ __forceinline__ unsigned xb_add(unsigned* p, unsigned v) { return __hip_atomic_fetch_add(p, v, __ATOMIC_RELAXED, __HIP_MEMORY_SCOPE_AGENT); }
; __device__ __forceinline__ void xcd_barrier(const XcdBarrier& b) {
;     ...
;         const unsigned old = xb_add(&bar[XB_XSUB(b.x)], 1u);
;         const unsigned gen = old / nloc;
.LBB0_365:
	s_mov_b64 s[8:9], exec
	s_lshl_b32 s6, s87, 8
	v_readlane_b32 s10, v240, 0
	v_mbcnt_lo_u32_b32 v1, s8, 0
	v_readlane_b32 s11, v240, 1
	s_add_u32 s6, s10, s6
	v_mbcnt_hi_u32_b32 v1, s9, v1
	s_addc_u32 s7, s11, 0
	v_cmp_eq_u32_e32 vcc, 0, v1
	s_and_saveexec_b64 s[12:13], vcc
	s_cbranch_execz .LBB0_367
	s_bcnt1_i32_b64 s8, s[8:9]
	v_mov_b32_e32 v3, 0x1000
	v_mov_b32_e32 v4, s8
	global_atomic_add v3, v3, v4, s[6:7] offset:1024 sc0
	buffer_inv sc1

; __device__ __forceinline__ unsigned xb_ld(unsigned* p)              { return __hip_atomic_load(p, __ATOMIC_RELAXED, __HIP_MEMORY_SCOPE_AGENT); }
; #define XB_SPIN(cond, bar) do { unsigned _sp = 0; while (cond) { __builtin_amdgcn_s_sleep(1); \
;     if ((++_sp & 255u) == 0u) { if (xb_ld(&(bar)[XB_TMO])) break; if (_sp > XB_SPIN_CAP) { atomicAdd(&(bar)[XB_TMO], 1u); break; } } } } while (0)
; __device__ __forceinline__ void xcd_barrier(const XcdBarrier& b) {
;     ...
;             XB_SPIN(xb_ld(&bar[XB_XGEN(b.x)]) == gen, bar);
;             __builtin_amdgcn_fence(__ATOMIC_ACQUIRE, "agent");
;             asm volatile("s_waitcnt vmcnt(0)" ::: "memory");
.LBB0_380:
	s_or_b64 exec, exec, s[12:13]
	s_waitcnt vmcnt(0)
	s_waitcnt vmcnt(0)

; __device__ __forceinline__ unsigned xb_add(unsigned* p, unsigned v) { return __hip_atomic_fetch_add(p, v, __ATOMIC_RELAXED, __HIP_MEMORY_SCOPE_AGENT); }
; __device__ __forceinline__ void xcd_barrier(const XcdBarrier& b) {
;     ...
;             xb_add(&bar[XB_XGEN(b.x)], 1u);
;             asm volatile("s_waitcnt vmcnt(0)" ::: "memory");
.LBB0_398:
	s_or_b64 exec, exec, s[8:9]
	s_mov_b64 s[8:9], exec
	v_mbcnt_lo_u32_b32 v0, s8, 0
	v_mbcnt_hi_u32_b32 v0, s9, v0
	v_cmp_eq_u32_e32 vcc, 0, v0
	s_waitcnt vmcnt(0)
	s_and_saveexec_b64 s[12:13], vcc
	s_cbranch_execz .LBB0_400
	s_bcnt1_i32_b64 s8, s[8:9]
	v_mov_b32_e32 v0, 0x2000
	v_mov_b32_e32 v1, s8
	global_atomic_add v0, v1, s[6:7] offset:1024
.LBB0_400:
	s_or_b64 exec, exec, s[12:13]
	s_waitcnt vmcnt(0)

; __device__ __forceinline__ unsigned xb_add(unsigned* p, unsigned v) { return __hip_atomic_fetch_add(p, v, __ATOMIC_RELAXED, __HIP_MEMORY_SCOPE_AGENT); }
; __device__ __forceinline__ void xcd_barrier(const XcdBarrier& b) {
;     ...
;             xb_add(&bar[XB_XGEN(b.x)], 1u);
;             asm volatile("s_waitcnt vmcnt(0)" ::: "memory");
.LBB0_463:
	s_or_b64 exec, exec, s[8:9]
	s_mov_b64 s[8:9], exec
	v_mbcnt_lo_u32_b32 v0, s8, 0
	v_mbcnt_hi_u32_b32 v0, s9, v0
	v_cmp_eq_u32_e32 vcc, 0, v0
	s_waitcnt vmcnt(0)
	s_and_saveexec_b64 s[12:13], vcc
	s_cbranch_execz .LBB0_465
	s_bcnt1_i32_b64 s8, s[8:9]
	v_mov_b32_e32 v0, 0x2000
	v_mov_b32_e32 v1, s8
	global_atomic_add v0, v1, s[6:7] offset:1024
.LBB0_465:
	s_or_b64 exec, exec, s[12:13]
	s_waitcnt vmcnt(0)

; __device__ __forceinline__ unsigned xb_ld(unsigned* p)              { return __hip_atomic_load(p, __ATOMIC_RELAXED, __HIP_MEMORY_SCOPE_AGENT); }
; __device__ __forceinline__ unsigned xb_add(unsigned* p, unsigned v) { return __hip_atomic_fetch_add(p, v, __ATOMIC_RELAXED, __HIP_MEMORY_SCOPE_AGENT); }
; #define XB_SPIN(cond, bar) do { unsigned _sp = 0; while (cond) { __builtin_amdgcn_s_sleep(1); \
;     if ((++_sp & 255u) == 0u) { if (xb_ld(&(bar)[XB_TMO])) break; if (_sp > XB_SPIN_CAP) { atomicAdd(&(bar)[XB_TMO], 1u); break; } } } } while (0)
; __device__ __forceinline__ void xcd_barrier(const XcdBarrier& b) {
;     ...
;         const unsigned old = xb_add(&bar[XB_XSUB(b.x)], 1u);
;         const unsigned gen = old / nloc;
;         if (old + 1u == (gen + 1u) * nloc) {
;             __builtin_amdgcn_fence(__ATOMIC_RELEASE, "agent");
;             asm volatile("s_waitcnt vmcnt(0)" ::: "memory");
;             const unsigned og = xb_add(&bar[XB_TOP], 1u);
;             const unsigned tg = og / nx;
;             if (og + 1u == (tg + 1u) * nx) xb_add(&bar[XB_TOPGEN], 1u);
;             else XB_SPIN(xb_ld(&bar[XB_TOPGEN]) == tg, bar);
;             __builtin_amdgcn_fence(__ATOMIC_ACQUIRE, "agent");
;             xb_add(&bar[XB_XGEN(b.x)], 1u);
;             asm volatile("s_waitcnt vmcnt(0)" ::: "memory");
;         } else {
;             XB_SPIN(xb_ld(&bar[XB_XGEN(b.x)]) == gen, bar);
.LBB0_484:
	v_readlane_b32 s6, v240, 2
	s_lshl_b32 s6, s6, 8
	s_add_u32 s6, s60, s6
	s_addc_u32 s7, s61, 0
	v_mov_b32_e32 v1, 0x1000
	v_mov_b32_e32 v3, 1
	global_atomic_add v3, v1, v3, s[6:7] offset:1024 sc0
	buffer_inv sc1
	v_cvt_f32_u32_e32 v1, v2
	v_sub_u32_e32 v4, 0, v2
	v_rcp_iflag_f32_e32 v1, v1
	s_nop 0
	v_mul_f32_e32 v1, 0x4f7ffffe, v1
	v_cvt_u32_f32_e32 v1, v1
	v_mul_lo_u32 v4, v4, v1
	v_mul_hi_u32 v4, v1, v4
	v_add_u32_e32 v1, v1, v4
	s_waitcnt vmcnt(0)
	v_mul_hi_u32 v1, v3, v1
	v_mul_lo_u32 v4, v1, v2
	v_sub_u32_e32 v4, v3, v4
	v_add_u32_e32 v5, 1, v1
	v_cmp_ge_u32_e32 vcc, v4, v2
	v_add_u32_e32 v3, 1, v3
	s_nop 0
	v_cndmask_b32_e32 v1, v1, v5, vcc
	v_sub_u32_e32 v5, v4, v2
	v_cndmask_b32_e32 v4, v4, v5, vcc
	v_add_u32_e32 v5, 1, v1
	v_cmp_ge_u32_e32 vcc, v4, v2
	s_nop 1
	v_cndmask_b32_e32 v1, v1, v5, vcc
	v_mul_lo_u32 v4, v2, v1
	v_add_u32_e32 v2, v4, v2
	v_cmp_ne_u32_e32 vcc, v3, v2
	s_and_saveexec_b64 s[8:9], vcc
	s_xor_b64 s[8:9], exec, s[8:9]
	s_cbranch_execz .LBB0_498
	s_waitcnt lgkmcnt(0)
	v_mov_b32_e32 v0, 0x2000
	global_load_dword v0, v0, s[6:7] offset:1024 sc1
	s_add_u32 s14, s6, 0x2400
	s_addc_u32 s15, s7, 0
	s_waitcnt vmcnt(0)
	v_cmp_eq_u32_e32 vcc, v0, v1
	s_and_saveexec_b64 s[12:13], vcc
	s_cbranch_execz .LBB0_497
	s_mov_b32 s10, 1
	s_mov_b64 s[16:17], 0
	v_mov_b32_e32 v0, 0
	s_branch .LBB0_488

; __device__ __forceinline__ unsigned xb_add(unsigned* p, unsigned v) { return __hip_atomic_fetch_add(p, v, __ATOMIC_RELAXED, __HIP_MEMORY_SCOPE_AGENT); }
; __device__ __forceinline__ void xcd_barrier(const XcdBarrier& b) {
;     ...
;             xb_add(&bar[XB_XGEN(b.x)], 1u);
;             asm volatile("s_waitcnt vmcnt(0)" ::: "memory");
.Lgb_skip_0:
	v_mov_b32_e32 v0, 0x2000
	v_mov_b32_e32 v1, 1
	s_waitcnt vmcnt(0)
	global_atomic_add v0, v1, s[6:7] offset:1024
	s_waitcnt vmcnt(0)

; __device__ __forceinline__ unsigned xb_add(unsigned* p, unsigned v) { return __hip_atomic_fetch_add(p, v, __ATOMIC_RELAXED, __HIP_MEMORY_SCOPE_AGENT); }
; __device__ __forceinline__ void xcd_barrier(const XcdBarrier& b) {
;     ...
;         const unsigned old = xb_add(&bar[XB_XSUB(b.x)], 1u);
;         const unsigned gen = old / nloc;
.LBB0_634:
	s_mov_b64 s[12:13], exec
	s_lshl_b32 s8, s87, 8
	v_readlane_b32 s10, v240, 0
	v_mbcnt_lo_u32_b32 v1, s12, 0
	v_readlane_b32 s11, v240, 1
	s_add_u32 s8, s10, s8
	v_mbcnt_hi_u32_b32 v1, s13, v1
	s_addc_u32 s9, s11, 0
	v_cmp_eq_u32_e32 vcc, 0, v1
	s_and_saveexec_b64 s[16:17], vcc
	s_cbranch_execz .LBB0_636
	s_bcnt1_i32_b64 s10, s[12:13]
	v_mov_b32_e32 v3, 0x1000
	v_mov_b32_e32 v4, s10
	global_atomic_add v3, v3, v4, s[8:9] offset:1024 sc0
	buffer_inv sc1

; __device__ __forceinline__ unsigned xb_ld(unsigned* p)              { return __hip_atomic_load(p, __ATOMIC_RELAXED, __HIP_MEMORY_SCOPE_AGENT); }
; #define XB_SPIN(cond, bar) do { unsigned _sp = 0; while (cond) { __builtin_amdgcn_s_sleep(1); \
;     if ((++_sp & 255u) == 0u) { if (xb_ld(&(bar)[XB_TMO])) break; if (_sp > XB_SPIN_CAP) { atomicAdd(&(bar)[XB_TMO], 1u); break; } } } } while (0)
; __device__ __forceinline__ void xcd_barrier(const XcdBarrier& b) {
;     ...
;             XB_SPIN(xb_ld(&bar[XB_XGEN(b.x)]) == gen, bar);
;             __builtin_amdgcn_fence(__ATOMIC_ACQUIRE, "agent");
;             asm volatile("s_waitcnt vmcnt(0)" ::: "memory");
.LBB0_649:
	s_or_b64 exec, exec, s[16:17]
	s_waitcnt vmcnt(0)
	s_waitcnt vmcnt(0)

; __device__ __forceinline__ unsigned xb_add(unsigned* p, unsigned v) { return __hip_atomic_fetch_add(p, v, __ATOMIC_RELAXED, __HIP_MEMORY_SCOPE_AGENT); }
; __device__ __forceinline__ void xcd_barrier(const XcdBarrier& b) {
;     ...
;             xb_add(&bar[XB_XGEN(b.x)], 1u);
;             asm volatile("s_waitcnt vmcnt(0)" ::: "memory");
.LBB0_667:
	s_or_b64 exec, exec, s[12:13]
	s_mov_b64 s[12:13], exec
	v_mbcnt_lo_u32_b32 v0, s12, 0
	v_mbcnt_hi_u32_b32 v0, s13, v0
	v_cmp_eq_u32_e32 vcc, 0, v0
	s_waitcnt vmcnt(0)
	s_and_saveexec_b64 s[16:17], vcc
	s_cbranch_execz .LBB0_669
	s_bcnt1_i32_b64 s10, s[12:13]
	v_mov_b32_e32 v0, 0x2000
	v_mov_b32_e32 v1, s10
	global_atomic_add v0, v1, s[8:9] offset:1024
.LBB0_669:
	s_or_b64 exec, exec, s[16:17]
	s_waitcnt vmcnt(0)

; __device__ __forceinline__ unsigned xb_ld(unsigned* p)              { return __hip_atomic_load(p, __ATOMIC_RELAXED, __HIP_MEMORY_SCOPE_AGENT); }
; __device__ __forceinline__ unsigned xb_add(unsigned* p, unsigned v) { return __hip_atomic_fetch_add(p, v, __ATOMIC_RELAXED, __HIP_MEMORY_SCOPE_AGENT); }
; #define XB_SPIN(cond, bar) do { unsigned _sp = 0; while (cond) { __builtin_amdgcn_s_sleep(1); \
;     if ((++_sp & 255u) == 0u) { if (xb_ld(&(bar)[XB_TMO])) break; if (_sp > XB_SPIN_CAP) { atomicAdd(&(bar)[XB_TMO], 1u); break; } } } } while (0)
; __device__ __forceinline__ void xcd_barrier(const XcdBarrier& b) {
;     ...
;         const unsigned old = xb_add(&bar[XB_XSUB(b.x)], 1u);
;         const unsigned gen = old / nloc;
;         if (old + 1u == (gen + 1u) * nloc) {
;             __builtin_amdgcn_fence(__ATOMIC_RELEASE, "agent");
;             asm volatile("s_waitcnt vmcnt(0)" ::: "memory");
;             const unsigned og = xb_add(&bar[XB_TOP], 1u);
;             const unsigned tg = og / nx;
;             if (og + 1u == (tg + 1u) * nx) xb_add(&bar[XB_TOPGEN], 1u);
;             else XB_SPIN(xb_ld(&bar[XB_TOPGEN]) == tg, bar);
;             __builtin_amdgcn_fence(__ATOMIC_ACQUIRE, "agent");
;             xb_add(&bar[XB_XGEN(b.x)], 1u);
;             asm volatile("s_waitcnt vmcnt(0)" ::: "memory");
;         } else {
;             XB_SPIN(xb_ld(&bar[XB_XGEN(b.x)]) == gen, bar);
.LBB0_731:
	v_readlane_b32 s4, v240, 2
	s_lshl_b32 s4, s4, 8
	s_add_u32 s4, s60, s4
	s_addc_u32 s5, s61, 0
	v_mov_b32_e32 v1, 0x1000
	v_mov_b32_e32 v3, 1
	global_atomic_add v3, v1, v3, s[4:5] offset:1024 sc0
	buffer_inv sc1
	v_cvt_f32_u32_e32 v1, v2
	v_sub_u32_e32 v4, 0, v2
	v_rcp_iflag_f32_e32 v1, v1
	s_nop 0
	v_mul_f32_e32 v1, 0x4f7ffffe, v1
	v_cvt_u32_f32_e32 v1, v1
	v_mul_lo_u32 v4, v4, v1
	v_mul_hi_u32 v4, v1, v4
	v_add_u32_e32 v1, v1, v4
	s_waitcnt vmcnt(0)
	v_mul_hi_u32 v1, v3, v1
	v_mul_lo_u32 v4, v1, v2
	v_sub_u32_e32 v4, v3, v4
	v_add_u32_e32 v5, 1, v1
	v_cmp_ge_u32_e32 vcc, v4, v2
	v_add_u32_e32 v3, 1, v3
	s_nop 0
	v_cndmask_b32_e32 v1, v1, v5, vcc
	v_sub_u32_e32 v5, v4, v2
	v_cndmask_b32_e32 v4, v4, v5, vcc
	v_add_u32_e32 v5, 1, v1
	v_cmp_ge_u32_e32 vcc, v4, v2
	s_nop 1
	v_cndmask_b32_e32 v1, v1, v5, vcc
	v_mul_lo_u32 v4, v2, v1
	v_add_u32_e32 v2, v4, v2
	v_cmp_ne_u32_e32 vcc, v3, v2
	s_and_saveexec_b64 s[6:7], vcc
	s_xor_b64 s[6:7], exec, s[6:7]
	s_cbranch_execz .LBB0_762
	s_waitcnt lgkmcnt(0)
	v_mov_b32_e32 v0, 0x2000
	global_load_dword v0, v0, s[4:5] offset:1024 sc1
	s_add_u32 s12, s4, 0x2400
	s_addc_u32 s13, s5, 0
	s_waitcnt vmcnt(0)
	v_cmp_eq_u32_e32 vcc, v0, v1
	s_and_saveexec_b64 s[8:9], vcc
	s_cbranch_execz .LBB0_761
	s_mov_b32 s10, 1
	s_mov_b64 s[16:17], 0
	v_mov_b32_e32 v0, 0
	s_branch .LBB0_735

; __device__ __forceinline__ unsigned xb_ld(unsigned* p)              { return __hip_atomic_load(p, __ATOMIC_RELAXED, __HIP_MEMORY_SCOPE_AGENT); }
; #define XB_SPIN(cond, bar) do { unsigned _sp = 0; while (cond) { __builtin_amdgcn_s_sleep(1); \
;     if ((++_sp & 255u) == 0u) { if (xb_ld(&(bar)[XB_TMO])) break; if (_sp > XB_SPIN_CAP) { atomicAdd(&(bar)[XB_TMO], 1u); break; } } } } while (0)
; __device__ __forceinline__ void xcd_barrier(const XcdBarrier& b) {
;     ...
;             XB_SPIN(xb_ld(&bar[XB_XGEN(b.x)]) == gen, bar);
;             __builtin_amdgcn_fence(__ATOMIC_ACQUIRE, "agent");
;             asm volatile("s_waitcnt vmcnt(0)" ::: "memory");
.LBB0_761:
	s_or_b64 exec, exec, s[8:9]
	s_waitcnt vmcnt(0)
	s_waitcnt vmcnt(0)

; __device__ __forceinline__ unsigned xb_add(unsigned* p, unsigned v) { return __hip_atomic_fetch_add(p, v, __ATOMIC_RELAXED, __HIP_MEMORY_SCOPE_AGENT); }
; __device__ __forceinline__ void xcd_barrier(const XcdBarrier& b) {
;     ...
;             xb_add(&bar[XB_XGEN(b.x)], 1u);
;             asm volatile("s_waitcnt vmcnt(0)" ::: "memory");
.LBB0_779:
	s_or_b64 exec, exec, s[12:13]
	s_mov_b64 s[12:13], exec
	v_mbcnt_lo_u32_b32 v0, s12, 0
	v_mbcnt_hi_u32_b32 v0, s13, v0
	v_cmp_eq_u32_e32 vcc, 0, v0
	s_waitcnt vmcnt(0)
	s_and_saveexec_b64 s[16:17], vcc
	s_cbranch_execz .LBB0_781
	s_bcnt1_i32_b64 s10, s[12:13]
	v_mov_b32_e32 v0, 0x2000
	v_mov_b32_e32 v1, s10
	global_atomic_add v0, v1, s[8:9] offset:1024
.LBB0_781:
	s_or_b64 exec, exec, s[16:17]
	s_waitcnt vmcnt(0)

; __device__ __forceinline__ unsigned xb_add(unsigned* p, unsigned v) { return __hip_atomic_fetch_add(p, v, __ATOMIC_RELAXED, __HIP_MEMORY_SCOPE_AGENT); }
; __device__ __forceinline__ void xcd_barrier(const XcdBarrier& b) {
;     ...
;             xb_add(&bar[XB_XGEN(b.x)], 1u);
;             asm volatile("s_waitcnt vmcnt(0)" ::: "memory");
.Lgb_skip_1:
	v_mov_b32_e32 v0, 0x2000
	v_mov_b32_e32 v1, 1
	s_waitcnt vmcnt(0)
	global_atomic_add v0, v1, s[4:5] offset:1024
	s_waitcnt vmcnt(0)

; __device__ __forceinline__ unsigned xb_add(unsigned* p, unsigned v) { return __hip_atomic_fetch_add(p, v, __ATOMIC_RELAXED, __HIP_MEMORY_SCOPE_AGENT); }
; __device__ __forceinline__ void xcd_barrier(const XcdBarrier& b) {
;     ...
;             xb_add(&bar[XB_XGEN(b.x)], 1u);
;             asm volatile("s_waitcnt vmcnt(0)" ::: "memory");
.LBB0_865:
	s_or_b64 exec, exec, s[8:9]
	s_mov_b64 s[8:9], exec
	v_mbcnt_lo_u32_b32 v0, s8, 0
	v_mbcnt_hi_u32_b32 v0, s9, v0
	v_cmp_eq_u32_e32 vcc, 0, v0
	s_waitcnt vmcnt(0)
	s_and_saveexec_b64 s[12:13], vcc
	s_cbranch_execz .LBB0_867
	s_bcnt1_i32_b64 s8, s[8:9]
	v_mov_b32_e32 v0, 0x2000
	v_mov_b32_e32 v1, s8
	global_atomic_add v0, v1, s[6:7] offset:1024
.LBB0_867:
	s_or_b64 exec, exec, s[12:13]
	s_waitcnt vmcnt(0)

; __device__ __forceinline__ unsigned xb_ld(unsigned* p)              { return __hip_atomic_load(p, __ATOMIC_RELAXED, __HIP_MEMORY_SCOPE_AGENT); }
; __device__ __forceinline__ unsigned xb_add(unsigned* p, unsigned v) { return __hip_atomic_fetch_add(p, v, __ATOMIC_RELAXED, __HIP_MEMORY_SCOPE_AGENT); }
; #define XB_SPIN(cond, bar) do { unsigned _sp = 0; while (cond) { __builtin_amdgcn_s_sleep(1); \
;     if ((++_sp & 255u) == 0u) { if (xb_ld(&(bar)[XB_TMO])) break; if (_sp > XB_SPIN_CAP) { atomicAdd(&(bar)[XB_TMO], 1u); break; } } } } while (0)
; __device__ __forceinline__ void xcd_barrier(const XcdBarrier& b) {
;     ...
;         const unsigned old = xb_add(&bar[XB_XSUB(b.x)], 1u);
;         const unsigned gen = old / nloc;
;         if (old + 1u == (gen + 1u) * nloc) {
;             __builtin_amdgcn_fence(__ATOMIC_RELEASE, "agent");
;             asm volatile("s_waitcnt vmcnt(0)" ::: "memory");
;             const unsigned og = xb_add(&bar[XB_TOP], 1u);
;             const unsigned tg = og / nx;
;             if (og + 1u == (tg + 1u) * nx) xb_add(&bar[XB_TOPGEN], 1u);
;             else XB_SPIN(xb_ld(&bar[XB_TOPGEN]) == tg, bar);
;             __builtin_amdgcn_fence(__ATOMIC_ACQUIRE, "agent");
;             xb_add(&bar[XB_XGEN(b.x)], 1u);
;             asm volatile("s_waitcnt vmcnt(0)" ::: "memory");
;         } else {
;             XB_SPIN(xb_ld(&bar[XB_XGEN(b.x)]) == gen, bar);
.LBB0_886:
	v_readlane_b32 s6, v240, 2
	s_lshl_b32 s6, s6, 8
	s_add_u32 s6, s60, s6
	s_addc_u32 s7, s61, 0
	v_mov_b32_e32 v1, 0x1000
	v_mov_b32_e32 v3, 1
	global_atomic_add v3, v1, v3, s[6:7] offset:1024 sc0
	buffer_inv sc1
	v_cvt_f32_u32_e32 v1, v2
	v_sub_u32_e32 v4, 0, v2
	v_rcp_iflag_f32_e32 v1, v1
	s_nop 0
	v_mul_f32_e32 v1, 0x4f7ffffe, v1
	v_cvt_u32_f32_e32 v1, v1
	v_mul_lo_u32 v4, v4, v1
	v_mul_hi_u32 v4, v1, v4
	v_add_u32_e32 v1, v1, v4
	s_waitcnt vmcnt(0)
	v_mul_hi_u32 v1, v3, v1
	v_mul_lo_u32 v4, v1, v2
	v_sub_u32_e32 v4, v3, v4
	v_add_u32_e32 v5, 1, v1
	v_cmp_ge_u32_e32 vcc, v4, v2
	v_add_u32_e32 v3, 1, v3
	s_nop 0
	v_cndmask_b32_e32 v1, v1, v5, vcc
	v_sub_u32_e32 v5, v4, v2
	v_cndmask_b32_e32 v4, v4, v5, vcc
	v_add_u32_e32 v5, 1, v1
	v_cmp_ge_u32_e32 vcc, v4, v2
	s_nop 1
	v_cndmask_b32_e32 v1, v1, v5, vcc
	v_mul_lo_u32 v4, v2, v1
	v_add_u32_e32 v2, v4, v2
	v_cmp_ne_u32_e32 vcc, v3, v2
	s_and_saveexec_b64 s[8:9], vcc
	s_xor_b64 s[8:9], exec, s[8:9]
	s_cbranch_execz .LBB0_900
	s_waitcnt lgkmcnt(0)
	v_mov_b32_e32 v0, 0x2000
	global_load_dword v0, v0, s[6:7] offset:1024 sc1
	s_add_u32 s16, s6, 0x2400
	s_addc_u32 s17, s7, 0
	s_waitcnt vmcnt(0)
	v_cmp_eq_u32_e32 vcc, v0, v1
	s_and_saveexec_b64 s[12:13], vcc
	s_cbranch_execz .LBB0_899
	s_mov_b32 s10, 1
	s_mov_b64 s[18:19], 0
	v_mov_b32_e32 v0, 0
	s_branch .LBB0_890

; __device__ __forceinline__ unsigned xb_add(unsigned* p, unsigned v) { return __hip_atomic_fetch_add(p, v, __ATOMIC_RELAXED, __HIP_MEMORY_SCOPE_AGENT); }
; __device__ __forceinline__ void xcd_barrier(const XcdBarrier& b) {
;     ...
;             xb_add(&bar[XB_XGEN(b.x)], 1u);
;             asm volatile("s_waitcnt vmcnt(0)" ::: "memory");
.LBB0_1006:
	s_or_b64 exec, exec, s[8:9]
	s_mov_b64 s[8:9], exec
	v_mbcnt_lo_u32_b32 v0, s8, 0
	v_mbcnt_hi_u32_b32 v0, s9, v0
	v_cmp_eq_u32_e32 vcc, 0, v0
	s_waitcnt vmcnt(0)
	s_and_saveexec_b64 s[12:13], vcc
	s_cbranch_execz .LBB0_1008
	s_bcnt1_i32_b64 s8, s[8:9]
	v_mov_b32_e32 v0, 0x2000
	v_mov_b32_e32 v1, s8
	global_atomic_add v0, v1, s[6:7] offset:1024
.LBB0_1008:
	s_or_b64 exec, exec, s[12:13]
	s_waitcnt vmcnt(0)

; __device__ __forceinline__ unsigned xb_add(unsigned* p, unsigned v) { return __hip_atomic_fetch_add(p, v, __ATOMIC_RELAXED, __HIP_MEMORY_SCOPE_AGENT); }
; __device__ __forceinline__ void xcd_barrier(const XcdBarrier& b) {
;     ...
;         const unsigned old = xb_add(&bar[XB_XSUB(b.x)], 1u);
;         const unsigned gen = old / nloc;
.LBB0_1176:
	s_mov_b64 s[6:7], exec
	s_lshl_b32 s4, s87, 8
	v_readlane_b32 s8, v240, 0
	v_mbcnt_lo_u32_b32 v1, s6, 0
	v_readlane_b32 s9, v240, 1
	s_add_u32 s4, s8, s4
	v_mbcnt_hi_u32_b32 v1, s7, v1
	s_addc_u32 s5, s9, 0
	v_cmp_eq_u32_e32 vcc, 0, v1
	s_and_saveexec_b64 s[8:9], vcc
	s_cbranch_execz .LBB0_1178
	s_bcnt1_i32_b64 s6, s[6:7]
	v_mov_b32_e32 v3, 0x1000
	v_mov_b32_e32 v4, s6
	global_atomic_add v3, v3, v4, s[4:5] offset:1024 sc0
	buffer_inv sc1

; __device__ __forceinline__ unsigned xb_add(unsigned* p, unsigned v) { return __hip_atomic_fetch_add(p, v, __ATOMIC_RELAXED, __HIP_MEMORY_SCOPE_AGENT); }
; __device__ __forceinline__ void xcd_barrier(const XcdBarrier& b) {
;     ...
;             xb_add(&bar[XB_XGEN(b.x)], 1u);
;             asm volatile("s_waitcnt vmcnt(0)" ::: "memory");
.LBB0_1209:
	s_or_b64 exec, exec, s[6:7]
	s_mov_b64 s[6:7], exec
	v_mbcnt_lo_u32_b32 v0, s6, 0
	v_mbcnt_hi_u32_b32 v0, s7, v0
	v_cmp_eq_u32_e32 vcc, 0, v0
	s_waitcnt vmcnt(0)
	s_and_saveexec_b64 s[8:9], vcc
	s_cbranch_execz .LBB0_1211
	s_bcnt1_i32_b64 s6, s[6:7]
	v_mov_b32_e32 v0, 0x2000
	v_mov_b32_e32 v1, s6
	global_atomic_add v0, v1, s[4:5] offset:1024
.LBB0_1211:
	s_or_b64 exec, exec, s[8:9]
	s_waitcnt vmcnt(0)
